# phase-scoped priority: equal priority for the two halves during G1+N1, first half raised again from G2+A2 on
# baseline (speedup 1.0000x reference)
; __device__ __forceinline__ int vblk() { return (int)blockIdx.x * 2 + half_id(); }
; __device__ __forceinline__ int vgrid() { return (int)gridDim.x * 2; }
; #define PF fresh_params()
; __device__ void phaseG1_task(const Params& p, int task, char* lds) {
;     const int tid = TIDX, lane = tid & 63, wave = tid >> 6, r = lane & 15, q = lane >> 4;
;     const int c = task & 31, h = (task >> 5) & 3, b = task >> 7;
;     const int tok0 = b * SEQ + c * 64;
;     const bf16_t* Z = (const bf16_t*)(p.ws + OFF_Z);
;     bf16_t* L = (bf16_t*)p.out;
;     float* bc = (float*)lds;
;     bf16_t* klT = (bf16_t*)(lds + 36864);
;     bf16_t* vT = (bf16_t*)(lds + 36864 + 18432);
;     gla_prep(p, tok0, h, lds);
;     if (tid < 128) ((float*)(p.ws + OFF_DEC))[task * 128 + tid] = __expf(bc[63 * 128 + tid]);
; __global__ void __launch_bounds__(BLOCK_THREADS, 2) mega(Params p_unused) {
;     ...
;     phaseC(PF, lds);
;     xcd_barrier(xb);
;     for (int task = vblk(); task < 1024; task += vgrid()) phaseG1_task(PF, task, hl);
.LBB0_376:
	s_or_b64 exec, exec, s[4:5]
	s_setprio 0
	s_getpc_b64 s[98:99]
	v_lshlrev_b32_e32 v250, 4, v158
	v_mov_b32_e32 v251, 0
	v_lshl_add_u64 v[250:251], s[98:99], 0, v[250:251]
	v_and_b32_e32 v250, -16, v250
	global_load_dwordx4 v[252:255], v[250:251], off
	v_lshl_add_u64 v[250:251], 64, 7, v[250:251]
	global_load_dwordx4 v[252:255], v[250:251], off
	v_lshl_add_u64 v[250:251], 64, 7, v[250:251]
	global_load_dwordx4 v[252:255], v[250:251], off
	v_lshl_add_u64 v[250:251], 64, 7, v[250:251]
	global_load_dwordx4 v[252:255], v[250:251], off
	v_readfirstlane_b32 s0, v158
	s_lshr_b32 s4, s0, 8
	s_add_i32 s14, s4, s85
	s_cmpk_gt_i32 s14, 0x3ff
	s_waitcnt lgkmcnt(0)
	s_barrier
	s_getpc_b64 s[98:99]
	v_lshlrev_b32_e32 v250, 4, v158
	v_mov_b32_e32 v251, 0
	v_lshl_add_u64 v[250:251], s[98:99], 0, v[250:251]
	v_and_b32_e32 v250, -16, v250
	global_load_dwordx4 v[252:255], v[250:251], off
	v_lshl_add_u64 v[250:251], 64, 7, v[250:251]
	global_load_dwordx4 v[252:255], v[250:251], off
	v_lshl_add_u64 v[250:251], 64, 7, v[250:251]
	global_load_dwordx4 v[252:255], v[250:251], off
	v_lshl_add_u64 v[250:251], 64, 7, v[250:251]
	global_load_dwordx4 v[252:255], v[250:251], off
	s_cbranch_scc1 .LBB0_387
	v_readlane_b32 s5, v222, 0
	s_lshl_b32 s2, s5, 5
	s_lshl_b32 s3, s4, 4
	s_lshl_b32 s5, s5, 7
	s_lshl_b32 s4, s4, 6
	s_lshl_b32 s0, s76, 1
	s_add_i32 s1, s33, 0x8000
	s_add_i32 s2, s2, s3
	s_lshl_b32 s3, s76, 5
	s_add_i32 s36, s5, s4
	s_lshl_b32 s37, s76, 7
	v_mov_b32_e32 v9, 0
	s_mov_b64 s[16:17], 0x5c02660
	s_movk_i32 s38, 0x2700
	s_movk_i32 s39, 0x2ff
	s_movk_i32 s40, 0x7f
	s_mov_b32 s19, 0
	s_mov_b32 s41, 0xbfb8aa3b
	s_mov_b32 s42, 0x800000
	s_mov_b32 s43, 0x3f317217
	s_mov_b32 s44, 0x7f800000
	v_mov_b32_e32 v20, 0x41b17218
	s_movk_i32 s45, 0x80
	s_mov_b64 s[20:21], 0x5c00000
	s_movk_i32 s46, 0x7fff
	s_mov_b64 s[22:23], 0x60
	s_mov_b64 s[24:25], 0x80
	s_mov_b64 s[26:27], 0xa0
	s_mov_b64 s[28:29], 0xc0
	s_mov_b64 s[30:31], 0xe0
	s_branch .LBB0_379

; __device__ __forceinline__ int vblk() { return (int)blockIdx.x * 2 + half_id(); }
; __device__ __forceinline__ int vgrid() { return (int)gridDim.x * 2; }
; #define PF fresh_params()
; __device__ void phaseG2(const Params& p) {
;     bf16_t* L = (bf16_t*)p.out;
;     const float* dec = (const float*)(p.ws + OFF_DEC);
;     for (int idx = vblk() * NTHREADS + (int)(threadIdx.x & 255); idx < 32 * 256 * 16; idx += vgrid() * NTHREADS) {
;         const int d8 = idx & 15, e = (idx >> 4) & 255, bh = idx >> 12;
; __global__ void __launch_bounds__(BLOCK_THREADS, 2) mega(Params p_unused) {
;     ...
;     for (int task = blockIdx.x; task < 256; task += gridDim.x) phaseN1_wg(PF, task, lds);
;     xcd_barrier(xb);
;     phaseG2(PF);
.LBB0_448:
	s_or_b64 exec, exec, s[4:5]
	v_readfirstlane_b32 s98, v158
	s_lshr_b32 s98, s98, 8
	s_cmp_eq_u32 s98, 0
	s_cbranch_scc0 .Lprio_g1_skip
	s_setprio 1
.Lprio_g1_skip:
	s_getpc_b64 s[98:99]
	v_lshlrev_b32_e32 v250, 4, v158
	v_mov_b32_e32 v251, 0
	v_lshl_add_u64 v[250:251], s[98:99], 0, v[250:251]
	v_and_b32_e32 v250, -16, v250
	global_load_dwordx4 v[252:255], v[250:251], off
	v_lshl_add_u64 v[250:251], 64, 7, v[250:251]
	global_load_dwordx4 v[252:255], v[250:251], off
	v_lshl_add_u64 v[250:251], 64, 7, v[250:251]
	global_load_dwordx4 v[252:255], v[250:251], off
	v_lshl_add_u64 v[250:251], 64, 7, v[250:251]
	global_load_dwordx4 v[252:255], v[250:251], off
	v_readfirstlane_b32 s0, v158
	v_readlane_b32 s1, v222, 0
	s_and_b32 s0, s0, 0xffffff00
	s_lshl_b32 s1, s1, 9
	s_add_i32 s0, s0, s1
	v_or_b32_sdwa v12, s0, v158 dst_sel:DWORD dst_unused:UNUSED_PAD src0_sel:DWORD src1_sel:BYTE_0
	s_mov_b32 s0, 0x20000
	s_mov_b64 s[10:11], s[80:81]
	v_cmp_gt_i32_e32 vcc, s0, v12
	s_waitcnt lgkmcnt(0)
	s_barrier
	s_getpc_b64 s[98:99]
	v_lshlrev_b32_e32 v250, 4, v158
	v_mov_b32_e32 v251, 0
	v_lshl_add_u64 v[250:251], s[98:99], 0, v[250:251]
	v_and_b32_e32 v250, -16, v250
	global_load_dwordx4 v[252:255], v[250:251], off
	v_lshl_add_u64 v[250:251], 64, 7, v[250:251]
	global_load_dwordx4 v[252:255], v[250:251], off
	v_lshl_add_u64 v[250:251], 64, 7, v[250:251]
	global_load_dwordx4 v[252:255], v[250:251], off
	v_lshl_add_u64 v[250:251], 64, 7, v[250:251]
	global_load_dwordx4 v[252:255], v[250:251], off
	s_and_saveexec_b64 s[8:9], vcc
	s_cbranch_execz .LBB0_453
	s_load_dwordx4 s[4:7], s[10:11], 0xd0
	s_lshl_b32 s0, s76, 9
	v_lshlrev_b32_e32 v13, 3, v12
	s_lshl_b32 s1, s76, 12
	s_mov_b64 s[10:11], 0
	s_movk_i32 s2, 0x1e0
	s_mov_b64 s[14:15], 0x1b4000
	s_mov_b32 s3, 0x1b4000
	s_mov_b32 s22, 0x10000
	s_mov_b64 s[16:17], 0x1b4200
	s_mov_b64 s[18:19], 0x20000
	s_mov_b32 s23, 0x1ffff
